# v72 + the 16 host workgroups keep only one P1b unit (third dropped unit to class-L workgroups 240..255), so the P3b unit they host no longer lengthens the P1b phase
# speedup vs baseline: 1.0164x; 1.0010x over previous
.Lp1be_ret:
	v_readlane_b32 s80, v254, 59
	v_readlane_b32 s83, v255, 6
	s_cmp_eq_u32 s98, 1
	s_cbranch_scc0 .Lp1be_done
	s_sub_u32 s101, s83, 0xd0
	s_cmp_gt_u32 s101, 47
	s_cbranch_scc1 .Lp1be_done
	s_lshl_b32 s99, s101, 1
	s_lshr_b32 s100, s101, 4
	s_mul_i32 s100, s100, 0x1e0
	s_addk_i32 s100, 0x101
	s_add_i32 s100, s100, s99
	s_lshr_b32 s99, s101, 5
	s_mul_i32 s99, s99, 0x500
	s_sub_i32 s100, s100, s99
	s_mov_b32 s83, s100
	s_add_i32 s99, s100, 1
	s_mov_b32 s98, 3
	s_branch .Lp1be_entry

.LBB0_547:
	s_or_b64 exec, exec, s[0:1]
	s_mov_b32 s98, 0
	s_movk_i32 s99, 0x600
	s_movk_i32 s100, 0x5ff
	s_cmpk_lg_u32 s80, 0x100
	s_cbranch_scc1 .Lp1be_entry
	s_movk_i32 s99, 0x400
	s_movk_i32 s100, 0x3ff
	s_and_b32 s101, s83, 1
	s_cmp_eq_u32 s101, 0
	s_cbranch_scc1 .Lp1be_entry
	s_cmpk_gt_u32 s83, 31
	s_cbranch_scc1 .Lp1be_entry
	s_movk_i32 s80, 0x200
	s_addk_i32 s83, 0x200

.LBB0_567:
	s_cmp_lg_u32 s98, 0
	s_cbranch_scc1 .Lp1be_ret
	v_readlane_b32 s80, v254, 59
	v_readlane_b32 s83, v255, 6
	s_cmpk_lg_u32 s80, 0x100
	s_cbranch_scc1 .Lp3be_skip
	s_and_b32 s101, s83, 1
	s_cmp_eq_u32 s101, 0
	s_cbranch_scc1 .Lp3be_skip
	s_cmpk_gt_u32 s83, 31
	s_cbranch_scc1 .Lp3be_skip
	s_mov_b32 s98, 2
	s_lshr_b32 s83, s83, 1
	s_addk_i32 s83, 0x200
	s_movk_i32 s99, 0x210
	s_movk_i32 s100, 0x20f
	s_branch .Lp3be_entry
